# stagger of the odd groups raised from 16us to 30us
# speedup vs baseline: 1.0105x; 1.0105x over previous
; __global__ void __launch_bounds__(NWAVES * 64, 2) hybrid_fwd(Args args) {
;     ...
;     if (IN(1)) {
;         pg8::Gemm g{Hb, (const bf16*)(ws + WS_WGU1), M, 2 * FF, D}; pg8::StaticOrder S; S.init(M, 2 * FF, G, (int)blockIdx.x);
;         pg8::EpiSwiGLU<false> E{ACT, FF, nullptr};
;         pg8::gemm_phase<pg8::EpiSwiGLU<false>, pg8::StaticOrder, true, true>(lds, g, S, E);
.Lstag0_loop:
	s_sleep 8
	s_memrealtime s[2:3]
	s_waitcnt lgkmcnt(0)
	s_sub_u32 s2, s2, s4
	s_cmp_lt_u32 s2, 3000
	s_cbranch_scc1 .Lstag0_loop
